# attention: bias table reads paired into ds_read2_b32
# baseline (speedup 1.0000x reference)
; #define MFMA32(a, b, c) __builtin_amdgcn_mfma_f32_32x32x16_bf16((a), (b), (c), 0, 0, 0)
; DI void attn_phase(LAS unsigned char* lds, ArgsRef a, int l, int vcu, int G) {
;     ...
;                 for (int c = 0; c < 4; ++c) s = MFMA32(kf[c], qf[c], s);
;                 float mx = -1e30f;
;                 if (loc) {
;                     const int tb = (h * 15 + (kr - row) + 7) * 31 + 15 - qcol + 32 * cb + 8 * hg;
;                     const int kc0 = 32 * cb + 8 * hg;
; #pragma unroll
;                     for (int r = 0; r < 4; ++r)
; #pragma unroll
;                         for (int i = 0; i < 4; ++i) {
;                             const int kt = 16 * (r >> 1) + 4 * (r & 1) + i, kc = kc0 + kt;
;                             const bool valid = (kc >= cs) && (kc < cs + 16);
;                             const float bias = tab[valid ? tb + kt : 0];
;                             const float v = valid ? s[4 * r + i] * SC + bias : -1e30f;
;                             s[4 * r + i] = v; mx = fmaxf(mx, v);
;                         }
.LBB0_352:
	s_waitcnt vmcnt(7) lgkmcnt(7)
	v_mfma_f32_32x32x16_bf16 v[64:79], v[144:147], v[96:99], 0
	s_mov_b64 s[6:7], -1
	s_and_b64 vcc, exec, s[8:9]
	s_waitcnt vmcnt(6) lgkmcnt(6)
	v_mfma_f32_32x32x16_bf16 v[64:79], v[148:151], v[100:103], v[64:79]
	s_waitcnt vmcnt(3) lgkmcnt(5)
	v_mfma_f32_32x32x16_bf16 v[64:79], v[152:155], v[112:115], v[64:79]
	s_waitcnt vmcnt(2) lgkmcnt(4)
	v_mfma_f32_32x32x16_bf16 v[64:79], v[156:159], v[116:119], v[64:79]
	s_cbranch_vccz .LBB0_386
	s_add_i32 s6, s39, s37
	s_lshl_b32 s12, s38, 5
	s_mul_i32 s6, s6, 31
	v_or_b32_e32 v90, s12, v217
	v_sub_u32_e32 v89, s6, v205
	s_lshl_b32 s13, s12, 2
	v_add_u32_e32 v89, v89, v217
	v_lshl_add_u32 v89, v89, 2, s13
	ds_read2_b32 v[80:81], v89 offset0:232 offset1:233
	ds_read2_b32 v[82:83], v89 offset0:234 offset1:235
	ds_read2_b32 v[84:85], v89 offset0:236 offset1:237
	ds_read2_b32 v[86:87], v89 offset0:238 offset1:239
	s_cmp_lg_u32 s38, 0
	s_cbranch_scc1 .LattnA_rd
	ds_read2_b32 v[206:207], v89 offset0:248 offset1:249
	ds_read2_b32 v[208:209], v89 offset0:250 offset1:251
	ds_read2_b32 v[210:211], v89 offset0:252 offset1:253
	ds_read2_b32 v[212:213], v89 offset0:254 offset1:255

; #define MFMA32(a, b, c) __builtin_amdgcn_mfma_f32_32x32x16_bf16((a), (b), (c), 0, 0, 0)
; DI void attn_phase(LAS unsigned char* lds, ArgsRef a, int l, int vcu, int G) {
;     ...
;                 for (int c = 0; c < 4; ++c) s = MFMA32(kf[c], qf[c], s);
;                 float mx = -1e30f;
;                 if (loc) {
;                     const int tb = (h * 15 + (kr - row) + 7) * 31 + 15 - qcol + 32 * cb + 8 * hg;
;                     const int kc0 = 32 * cb + 8 * hg;
; #pragma unroll
;                     for (int r = 0; r < 4; ++r)
; #pragma unroll
;                         for (int i = 0; i < 4; ++i) {
;                             const int kt = 16 * (r >> 1) + 4 * (r & 1) + i, kc = kc0 + kt;
;                             const bool valid = (kc >= cs) && (kc < cs + 16);
;                             const float bias = tab[valid ? tb + kt : 0];
;                             const float v = valid ? s[4 * r + i] * SC + bias : -1e30f;
;                             s[4 * r + i] = v; mx = fmaxf(mx, v);
;                         }
.LBB0_396:
	v_mfma_f32_32x32x16_bf16 v[64:79], v[144:147], v[104:107], 0
	s_mov_b64 s[6:7], -1
	s_and_b64 vcc, exec, s[8:9]
	v_mfma_f32_32x32x16_bf16 v[64:79], v[148:151], v[108:111], v[64:79]
	s_waitcnt vmcnt(1)
	v_mfma_f32_32x32x16_bf16 v[64:79], v[152:155], v[120:123], v[64:79]
	s_waitcnt vmcnt(0)
	v_mfma_f32_32x32x16_bf16 v[64:79], v[156:159], v[124:127], v[64:79]
	s_cbranch_vccz .LBB0_430
	s_add_i32 s6, s39, s37
	s_lshl_b32 s8, s38, 5
	s_mul_i32 s6, s6, 31
	v_or_b32_e32 v90, s8, v217
	v_sub_u32_e32 v88, s6, v205
	s_lshl_b32 s9, s8, 2
	v_add_u32_e32 v88, v88, v217
	v_lshl_add_u32 v88, v88, 2, s9
	ds_read2_b32 v[80:81], v88 offset0:216 offset1:217
	ds_read2_b32 v[82:83], v88 offset0:218 offset1:219
	ds_read2_b32 v[84:85], v88 offset0:220 offset1:221
	ds_read2_b32 v[86:87], v88 offset0:222 offset1:223
	s_cmp_eq_u32 s38, 0
	s_cbranch_scc1 .LattnB_rd
	ds_read2_b32 v[144:145], v88 offset0:200 offset1:201
	ds_read2_b32 v[146:147], v88 offset0:202 offset1:203
	ds_read2_b32 v[148:149], v88 offset0:204 offset1:205
	ds_read2_b32 v[150:151], v88 offset0:206 offset1:207
